# attention loop: K-fragment LDS addresses computed once per 64-key tile (reused by the second sub-tile), the 4 LDS-DMA pieces of tile T+2 interleaved into the first four PV MFMA gaps after the tile bar
# speedup vs baseline: 1.0164x; 1.0062x over previous
; #define LAS __attribute__((address_space(3)))
; #define DIFF_ISSUE(T_) do { const unsigned sb_ = lbase + (unsigned)((T_) & 3) * 32768u; const bf16* k_ = gk + (size_t)(T_) * (64 * 512); const bf16* v_ = gv + (size_t)(T_) * 64; \
;         glds16(k_, sb_); glds16(k_ + 64, sb_ + 8192u); glds16(v_, sb_ + 16384u); glds16(v_ + (size_t)64 * VPITCH, sb_ + 24576u); } while (0)
; __device__ __forceinline__ void diff_unit_lds(LAS unsigned char* lds, const bf16* Qd, const bf16* Kd, const bf16* VdT, bf16* MIX, const float* ghead, float lam, int head, int u, int wave, int lane) {
;     const int h = lane >> 5, r = lane & 31, kap = kappa(r), slot = wave & 3, comp = wave >> 2;
;     const int row = 128 * u + 32 * slot + r;
;     const int nT = 2 * u + 3, Tlast = 2 * u + 1 + (slot >> 1);
;     const bf16* qrow = Qd + (size_t)row * 512 + head * 128 + comp * 64;
;     bf16x8 qf[4];
; #pragma unroll
;     for (int ds = 0; ds < 4; ++ds) qf[ds] = *(const bf16x8*)(qrow + 16 * ds + 8 * h);
;     const int koff = comp * 8192 + kap * 128, kx = (kap >> 1) & 7;
;     const int voff = 16384 + r * 128, vx = (r >> 1) & 7;
;     const int srow = 8 * wave + (lane >> 3), sc = (lane & 7) ^ ((srow >> 1) & 7);
;     const bf16* gk = Kd + (size_t)srow * 512 + head * 128 + sc * 8;
;     const bf16* gv = VdT + (size_t)(head * 128 + srow) * VPITCH + sc * 8;
;     const unsigned lbase = (unsigned)(size_t)lds + (unsigned)wave * 1024u;
;     ...
;     f32x16 O[4]; float m_used = 0.f, l = 0.f;
;     f32x16 NEGM;
; #pragma unroll
;     for (int i = 0; i < 16; ++i) NEGM[i] = 0.f;
; #pragma unroll
;     for (int b = 0; b < 4; ++b)
; #pragma unroll
;         for (int i = 0; i < 16; ++i) O[b][i] = 0.f;
;     asm volatile("" : "+v"(qf[0]), "+v"(qf[1]), "+v"(qf[2]), "+v"(qf[3]));
;     asm volatile("s_waitcnt vmcnt(0)" ::: "memory");
;     DIFF_ISSUE(0); DIFF_ISSUE(1);
; #pragma unroll 2
;     for (int T = 0; T < nT; ++T) {
;         LAS unsigned char* st = lds + (T & 3) * 32768;
;         if ((T & 1) == 0) {
;             asm volatile("s_waitcnt vmcnt(0) lgkmcnt(0)\n\ts_barrier" ::: "memory");
;             if (T + 2 < nT) DIFF_ISSUE(T + 2);
;             if (T + 3 < nT) DIFF_ISSUE(T + 3);
.LBB0_452:
	s_and_b64 s[0:1], s[34:35], exec
	s_cselect_b32 s0, s89, s90
	v_lshl_or_b32 v190, s0, 7, v139
	v_ashrrev_i32_e32 v191, 31, v190
	v_lshlrev_b64 v[2:3], 10, v[190:191]
	v_lshl_add_u64 v[2:3], v[154:155], 0, v[2:3]
	global_load_dwordx4 v[114:117], v[2:3], off offset:96
	global_load_dwordx4 v[118:121], v[2:3], off offset:64
	global_load_dwordx4 v[122:125], v[2:3], off offset:32
	global_load_dwordx4 v[126:129], v[2:3], off
	v_mov_b32_e32 v65, 0
	v_mov_b32_e32 v64, 0
	v_mov_b32_e32 v63, 0
	v_mov_b32_e32 v62, 0
	v_mov_b32_e32 v61, 0
	v_mov_b32_e32 v60, 0
	v_mov_b32_e32 v59, 0
	v_mov_b32_e32 v58, 0
	v_mov_b32_e32 v57, 0
	v_mov_b32_e32 v56, 0
	v_mov_b32_e32 v55, 0
	v_mov_b32_e32 v54, 0
	v_mov_b32_e32 v53, 0
	v_mov_b32_e32 v52, 0
	v_mov_b32_e32 v51, 0
	v_mov_b32_e32 v50, 0
	v_mov_b32_e32 v49, 0
	v_mov_b32_e32 v48, 0
	v_mov_b32_e32 v47, 0
	v_mov_b32_e32 v46, 0
	v_mov_b32_e32 v45, 0
	v_mov_b32_e32 v44, 0
	v_mov_b32_e32 v43, 0
	v_mov_b32_e32 v42, 0
	v_mov_b32_e32 v41, 0
	v_mov_b32_e32 v40, 0
	v_mov_b32_e32 v39, 0
	v_mov_b32_e32 v38, 0
	v_mov_b32_e32 v37, 0
	v_mov_b32_e32 v36, 0
	v_mov_b32_e32 v35, 0
	v_mov_b32_e32 v34, 0
	v_mov_b32_e32 v33, 0
	v_mov_b32_e32 v32, 0
	v_mov_b32_e32 v31, 0
	v_mov_b32_e32 v30, 0
	v_mov_b32_e32 v29, 0
	v_mov_b32_e32 v28, 0
	v_mov_b32_e32 v27, 0
	v_mov_b32_e32 v26, 0
	v_mov_b32_e32 v25, 0
	v_mov_b32_e32 v24, 0
	v_mov_b32_e32 v23, 0
	v_mov_b32_e32 v22, 0
	v_mov_b32_e32 v21, 0
	v_mov_b32_e32 v20, 0
	v_mov_b32_e32 v19, 0
	v_mov_b32_e32 v18, 0
	v_mov_b32_e32 v17, 0
	v_mov_b32_e32 v16, 0
	v_mov_b32_e32 v15, 0
	v_mov_b32_e32 v14, 0
	v_mov_b32_e32 v13, 0
	v_mov_b32_e32 v12, 0
	v_mov_b32_e32 v11, 0
	v_mov_b32_e32 v10, 0
	v_mov_b32_e32 v9, 0
	v_mov_b32_e32 v8, 0
	v_mov_b32_e32 v7, 0
	v_mov_b32_e32 v6, 0
	v_mov_b32_e32 v5, 0
	s_cmp_lt_i32 s0, -1
	v_mov_b32_e32 v4, 0
	v_mov_b32_e32 v3, 0
	v_mov_b32_e32 v2, 0
	v_mov_b32_e32 v218, 0
	s_waitcnt vmcnt(0)
	s_waitcnt vmcnt(0)
	s_mov_b32 s56, s0
	s_mov_b32 s7, m0
	s_mov_b32 s8, 0x0
	s_mov_b32 s9, 0
	v_lshl_add_u64 v[180:181], v[158:159], 0, s[8:9]
	s_add_i32 s0, s33, 0x0
	s_mov_b32 m0, s0
	s_nop 0
	global_load_lds_dwordx4 v[180:181], off
	s_mov_b32 s8, 0x80
	s_mov_b32 s9, 0
	v_lshl_add_u64 v[182:183], v[158:159], 0, s[8:9]
	s_add_i32 s0, s33, 0x2000
	s_mov_b32 m0, s0
	s_nop 0
	global_load_lds_dwordx4 v[182:183], off
	s_mov_b32 s8, 0x0
	s_mov_b32 s9, 0
	v_lshl_add_u64 v[184:185], v[156:157], 0, s[8:9]
	s_add_i32 s0, s33, 0x4000
	s_mov_b32 m0, s0
	s_nop 0
	global_load_lds_dwordx4 v[184:185], off
	s_mov_b32 s8, 0x0
	s_mov_b32 s9, 0
	v_lshl_add_u64 v[186:187], v[162:163], 0, s[8:9]
	s_add_i32 s0, s33, 0x6000
	s_mov_b32 m0, s0
	s_nop 0
	global_load_lds_dwordx4 v[186:187], off
	s_mov_b32 s8, 0x10000
	s_mov_b32 s9, 0
	v_lshl_add_u64 v[180:181], v[158:159], 0, s[8:9]
	s_add_i32 s0, s33, 0x8000
	s_mov_b32 m0, s0
	s_nop 0
	global_load_lds_dwordx4 v[180:181], off
	s_mov_b32 s8, 0x10080
	s_mov_b32 s9, 0
	v_lshl_add_u64 v[182:183], v[158:159], 0, s[8:9]
	s_add_i32 s0, s33, 0xa000
	s_mov_b32 m0, s0
	s_nop 0
	global_load_lds_dwordx4 v[182:183], off
	s_mov_b32 s8, 0x80
	s_mov_b32 s9, 0
	v_lshl_add_u64 v[184:185], v[156:157], 0, s[8:9]
	s_add_i32 s0, s33, 0xc000
	s_mov_b32 m0, s0
	s_nop 0
	global_load_lds_dwordx4 v[184:185], off
	s_mov_b32 s8, 0x80
	s_mov_b32 s9, 0
	v_lshl_add_u64 v[186:187], v[162:163], 0, s[8:9]
	s_add_i32 s0, s33, 0xe000
	s_mov_b32 m0, s0
	s_nop 0
	global_load_lds_dwordx4 v[186:187], off
	s_waitcnt vmcnt(0) lgkmcnt(0)
	s_barrier
	s_mov_b32 s8, 0x20000
	s_mov_b32 s9, 0
	v_lshl_add_u64 v[180:181], v[158:159], 0, s[8:9]
	s_add_i32 s0, s33, 0x10000
	s_mov_b32 m0, s0
	s_nop 0
	global_load_lds_dwordx4 v[180:181], off
	s_mov_b32 s8, 0x20080
	s_mov_b32 s9, 0
	v_lshl_add_u64 v[182:183], v[158:159], 0, s[8:9]
	s_add_i32 s0, s33, 0x12000
	s_mov_b32 m0, s0
	s_nop 0
	global_load_lds_dwordx4 v[182:183], off
	s_mov_b32 s8, 0x100
	s_mov_b32 s9, 0
	v_lshl_add_u64 v[184:185], v[156:157], 0, s[8:9]
	s_add_i32 s0, s33, 0x14000
	s_mov_b32 m0, s0
	s_nop 0
	global_load_lds_dwordx4 v[184:185], off
	s_mov_b32 s8, 0x100
	s_mov_b32 s9, 0
	v_lshl_add_u64 v[186:187], v[162:163], 0, s[8:9]
	s_add_i32 s0, s33, 0x16000
	s_mov_b32 m0, s0
	s_nop 0
	global_load_lds_dwordx4 v[186:187], off
	s_cmp_lt_i32 s56, 1
	s_cbranch_scc1 .Lq_no_t3
	s_mov_b32 s8, 0x30000
	s_mov_b32 s9, 0
	v_lshl_add_u64 v[180:181], v[158:159], 0, s[8:9]
	s_add_i32 s0, s33, 0x18000
	s_mov_b32 m0, s0
	s_nop 0
	global_load_lds_dwordx4 v[180:181], off
	s_mov_b32 s8, 0x30080
	s_mov_b32 s9, 0
	v_lshl_add_u64 v[182:183], v[158:159], 0, s[8:9]
	s_add_i32 s0, s33, 0x1a000
	s_mov_b32 m0, s0
	s_nop 0
	global_load_lds_dwordx4 v[182:183], off
	s_mov_b32 s8, 0x180
	s_mov_b32 s9, 0
	v_lshl_add_u64 v[184:185], v[156:157], 0, s[8:9]
	s_add_i32 s0, s33, 0x1c000
	s_mov_b32 m0, s0
	s_nop 0
	global_load_lds_dwordx4 v[184:185], off
	s_mov_b32 s8, 0x180
	s_mov_b32 s9, 0
	v_lshl_add_u64 v[186:187], v[162:163], 0, s[8:9]
	s_add_i32 s0, s33, 0x1e000
	s_mov_b32 m0, s0
	s_nop 0
	global_load_lds_dwordx4 v[186:187], off
; #define LAS __attribute__((address_space(3)))
; #define MFMA32(a, b, c) __builtin_amdgcn_mfma_f32_32x32x16_bf16((a), (b), (c), 0, 0, 0)
; __device__ __forceinline__ void diff_unit_lds(LAS unsigned char* lds, const bf16* Qd, const bf16* Kd, const bf16* VdT, bf16* MIX, const float* ghead, float lam, int head, int u, int wave, int lane) {
;     ...
;         if (T <= Tlast) {
;             const bool part = (T == Tlast);
;             const bool masked = part && (h == 1);
;             f32x16 S0 = NEGM, S1 = NEGM;
; #pragma unroll
;             for (int ds = 0; ds < 4; ++ds) S0 = MFMA32(*(const LAS bf16x8*)(st + koff + (((2 * ds + h) ^ kx) << 4)), qf[ds], S0);
;             if (!part) {
; #pragma unroll
;                 for (int ds = 0; ds < 4; ++ds) S1 = MFMA32(*(const LAS bf16x8*)(st + koff + 4096 + (((2 * ds + h) ^ kx) << 4)), qf[ds], S1);
;             }
;             float tmax = S0[0];
; #pragma unroll
;             for (int i = 1; i < 16; ++i) tmax = fmaxf(tmax, S0[i]);
;             if (masked) tmax = -1e30f;
;             if (!part) {
; #pragma unroll
;                 for (int i = 0; i < 16; ++i) tmax = fmaxf(tmax, S1[i]);
;             }
;             tmax = fmaxf(tmax, xhalf(tmax, h));
;             if (T == 0 || __any(tmax > 8.0f)) {
;                 const float delta = (T == 0) ? tmax : fmaxf(tmax, 0.f), alpha = (T == 0) ? 1.0f : __builtin_amdgcn_exp2f(-delta);
;                 l *= alpha;
; #pragma unroll
;                 for (int b = 0; b < 4; ++b)
; #pragma unroll
;                     for (int i = 0; i < 16; ++i) O[b][i] *= alpha;
;                 m_used += delta;
; #pragma unroll
;                 for (int i = 0; i < 16; ++i) { NEGM[i] = -m_used; S0[i] -= delta; S1[i] -= delta; }
;             }
.Lq_no_t3:
	s_mov_b32 m0, s7
	s_lshl_b32 s93, s56, 1
	s_or_b32 s91, s23, s93
	s_add_i32 s91, s91, 1
	s_lshl_b32 s92, s91, 1
	s_mov_b32 s94, 0
	s_mov_b32 s96, 0xff800000
	s_mov_b32 s97, 0xff800000
	s_mov_b32 s59, 0
	v_mov_b32_e32 v66, 0
	v_mov_b32_e32 v67, 0
	v_mov_b32_e32 v68, 0
	v_mov_b32_e32 v69, 0
	v_mov_b32_e32 v70, 0
	v_mov_b32_e32 v71, 0
	v_mov_b32_e32 v72, 0
	v_mov_b32_e32 v73, 0
	v_mov_b32_e32 v74, 0
	v_mov_b32_e32 v75, 0
	v_mov_b32_e32 v76, 0
	v_mov_b32_e32 v77, 0
	v_mov_b32_e32 v78, 0
	v_mov_b32_e32 v79, 0
	v_mov_b32_e32 v80, 0
	v_mov_b32_e32 v81, 0
	v_mov_b32_e32 v219, 0
	v_mov_b32_e32 v82, 0
	v_mov_b32_e32 v83, 0
	v_mov_b32_e32 v84, 0
	v_mov_b32_e32 v85, 0
	v_mov_b32_e32 v86, 0
	v_mov_b32_e32 v87, 0
	v_mov_b32_e32 v88, 0
	v_mov_b32_e32 v89, 0
	v_mov_b32_e32 v220, 0
	v_mov_b32_e32 v221, 0
	v_mov_b32_e32 v222, 0
	v_mov_b32_e32 v223, 0
	v_mov_b32_e32 v226, 0
	v_mov_b32_e32 v227, 0
	v_mov_b32_e32 v228, 0
	v_mov_b32_e32 v229, 0
	v_mov_b32_e32 v230, 0
	v_mov_b32_e32 v231, 0
	v_mov_b32_e32 v232, 0
	v_mov_b32_e32 v233, 0
	v_mov_b32_e32 v234, 0
	v_mov_b32_e32 v235, 0
	v_mov_b32_e32 v236, 0
	v_mov_b32_e32 v237, 0
	v_mov_b32_e32 v238, 0
	v_mov_b32_e32 v239, 0
	v_mov_b32_e32 v240, 0
	v_mov_b32_e32 v241, 0
	v_mov_b32_e32 v242, 0
	v_mov_b32_e32 v243, 0
	v_mov_b32_e32 v244, 0
	v_mov_b32_e32 v245, 0
	v_mov_b32_e32 v246, 0
	v_mov_b32_e32 v247, 0
	v_mov_b32_e32 v248, 0
	v_mov_b32_e32 v249, 0
	v_mov_b32_e32 v252, 0
	v_mov_b32_e32 v253, 0
	v_mov_b32_e32 v254, 0
	v_mov_b32_e32 v255, 0
	v_mov_b32_e32 v203, v209
	v_mov_b32_e32 v204, v210
	v_mov_b32_e32 v192, v211
	v_mov_b32_e32 v193, v212
	ds_read_b128 v[164:167], v203
	ds_read_b128 v[168:171], v204
	ds_read_b128 v[172:175], v192
	ds_read_b128 v[176:179], v193
	s_waitcnt lgkmcnt(3)
	v_mfma_f32_32x32x16_bf16 v[98:113], v[164:167], v[126:129], v[66:81]
	s_waitcnt lgkmcnt(2)
	v_mfma_f32_32x32x16_bf16 v[98:113], v[168:171], v[122:125], v[98:113]
	s_waitcnt lgkmcnt(1)
	v_mfma_f32_32x32x16_bf16 v[98:113], v[172:175], v[118:121], v[98:113]
	s_waitcnt lgkmcnt(0)
	v_mfma_f32_32x32x16_bf16 v[98:113], v[176:179], v[114:117], v[98:113]
	s_nop 3
.Lq_even_top:
	s_cmp_eq_u32 s94, s92
	s_cbranch_scc1 .Lq_last
	s_lshr_b32 s0, s94, 1
	s_and_b32 s0, s0, 3
	s_lshl_b32 s95, s0, 15
	ds_read_b128 v[164:167], v203 offset:4096
	ds_read_b128 v[168:171], v204 offset:4096
	ds_read_b128 v[172:175], v192 offset:4096
	ds_read_b128 v[176:179], v193 offset:4096
	v_add_u32_e32 v208, s95, v133
	v_add_u32_e32 v213, s95, v205
	s_waitcnt lgkmcnt(4)
	v_mfma_f32_32x32x16_bf16 v[50:65], v[220:223], v[82:85], v[50:65]
	ds_read_b128 v[220:223], v208 offset:16384
	v_max3_f32 v1, v98, v99, v100
	v_max3_f32 v1, v1, v101, v102
	v_max3_f32 v1, v1, v103, v104
	v_max3_f32 v1, v1, v105, v106
	v_max3_f32 v1, v1, v107, v108
	v_mfma_f32_32x32x16_bf16 v[34:49], v[226:229], v[82:85], v[34:49]
	ds_read_b128 v[226:229], v208 offset:20480
	v_max3_f32 v1, v1, v109, v110
	v_max3_f32 v1, v1, v111, v112
	v_max_f32_e32 v224, v1, v113
	v_max_f32_e32 v225, v1, v113
	v_mfma_f32_32x32x16_bf16 v[18:33], v[230:233], v[82:85], v[18:33]
	ds_read_b128 v[230:233], v208 offset:24576
	s_nop 1
	v_permlane32_swap_b32_e32 v224, v225
	v_max_f32_e32 v1, v224, v225
	v_cmp_lt_f32_e32 vcc, s96, v1
	s_cbranch_vccnz .Lq_re_e

; #define LAS __attribute__((address_space(3)))
; #define MFMA32(a, b, c) __builtin_amdgcn_mfma_f32_32x32x16_bf16((a), (b), (c), 0, 0, 0)
; __device__ __forceinline__ void diff_unit_lds(LAS unsigned char* lds, const bf16* Qd, const bf16* Kd, const bf16* VdT, bf16* MIX, const float* ghead, float lam, int head, int u, int wave, int lane) {
;     ...
;             if (!part) {
;                 float p[16]; float ps = 0.f;
; #pragma unroll
;                 for (int i = 0; i < 16; ++i) { p[i] = __builtin_amdgcn_exp2f(S1[i]); ps += p[i]; }
;                 l += ps;
;                 const bf16x8 pk0 = pack8(p[0], p[1], p[2], p[3], p[4], p[5], p[6], p[7]);
;                 const bf16x8 pk1 = pack8(p[8], p[9], p[10], p[11], p[12], p[13], p[14], p[15]);
; #pragma unroll
;                 for (int b = 0; b < 4; ++b) {
;                     const bf16x8 v0 = *(const LAS bf16x8*)(st + voff + b * 4096 + (((4 + 2 * h) ^ vx) << 4));
;                     const bf16x8 v1 = *(const LAS bf16x8*)(st + voff + b * 4096 + (((4 + 2 * h + 1) ^ vx) << 4));
;                     O[b] = MFMA32(v0, pk0, O[b]); O[b] = MFMA32(v1, pk1, O[b]);
;                 }
;             }
.Lq_rlc_e:
	s_waitcnt lgkmcnt(8)
	v_mfma_f32_32x32x16_bf16 v[82:97], v[164:167], v[126:129], v[66:81]
	v_exp_f32_e32 v109, v109
	v_add_f32_e32 v251, v251, v107
	v_exp_f32_e32 v110, v110
	v_add_f32_e32 v251, v251, v108
	v_mfma_f32_32x32x16_bf16 v[82:97], v[168:171], v[122:125], v[82:97]
	v_exp_f32_e32 v111, v111
	v_add_f32_e32 v251, v251, v109
	v_exp_f32_e32 v112, v112
	v_add_f32_e32 v251, v251, v110
	v_mfma_f32_32x32x16_bf16 v[82:97], v[172:175], v[118:121], v[82:97]
	v_exp_f32_e32 v113, v113
	v_add_f32_e32 v251, v251, v111
	v_cvt_pk_bf16_f32 v102, v106, v107
	v_add_f32_e32 v251, v251, v112
	v_mfma_f32_32x32x16_bf16 v[82:97], v[176:179], v[114:117], v[82:97]
	v_cvt_pk_bf16_f32 v103, v108, v109
	v_cvt_pk_bf16_f32 v104, v110, v111
	v_cvt_pk_bf16_f32 v105, v112, v113
	v_add_f32_e32 v251, v251, v113
	v_add_f32_e32 v218, v218, v251
	s_add_i32 s94, s94, 1
	s_add_i32 s0, s94, 1
	s_lshr_b32 s57, s0, 1
	s_add_i32 s1, s93, 1
	s_cmp_le_u32 s57, s1
	s_cbranch_scc1 .Lq_w4
	s_waitcnt vmcnt(0)
	s_branch .Lq_wd

; __device__ __forceinline__ void diff_unit_lds(LAS unsigned char* lds, const bf16* Qd, const bf16* Kd, const bf16* VdT, bf16* MIX, const float* ghead, float lam, int head, int u, int wave, int lane) {
;     ...
;     for (int T = 0; T < nT; ++T) {
;         LAS unsigned char* st = lds + (T & 3) * 32768;
;         if ((T & 1) == 0) {
;             asm volatile("s_waitcnt vmcnt(0) lgkmcnt(0)\n\ts_barrier" ::: "memory");
;             if (T + 2 < nT) DIFF_ISSUE(T + 2);
;             if (T + 3 < nT) DIFF_ISSUE(T + 3);
;         }
;         if (T <= Tlast) {
;             const bool part = (T == Tlast);
;             const bool masked = part && (h == 1);
;             f32x16 S0 = NEGM, S1 = NEGM;
; #pragma unroll
;             for (int ds = 0; ds < 4; ++ds) S0 = MFMA32(*(const LAS bf16x8*)(st + koff + (((2 * ds + h) ^ kx) << 4)), qf[ds], S0);
;             if (!part) {
; #pragma unroll
;                 for (int ds = 0; ds < 4; ++ds) S1 = MFMA32(*(const LAS bf16x8*)(st + koff + 4096 + (((2 * ds + h) ^ kx) << 4)), qf[ds], S1);
;             }
;             float tmax = S0[0];
; #pragma unroll
;             for (int i = 1; i < 16; ++i) tmax = fmaxf(tmax, S0[i]);
;             if (masked) tmax = -1e30f;
;             if (!part) {
; #pragma unroll
;                 for (int i = 0; i < 16; ++i) tmax = fmaxf(tmax, S1[i]);
;             }
;             tmax = fmaxf(tmax, xhalf(tmax, h));
;             if (T == 0 || __any(tmax > 8.0f)) {
;                 const float delta = (T == 0) ? tmax : fmaxf(tmax, 0.f), alpha = (T == 0) ? 1.0f : __builtin_amdgcn_exp2f(-delta);
;                 l *= alpha;
; #pragma unroll
;                 for (int b = 0; b < 4; ++b)
; #pragma unroll
;                     for (int i = 0; i < 16; ++i) O[b][i] *= alpha;
;                 m_used += delta;
; #pragma unroll
;                 for (int i = 0; i < 16; ++i) { NEGM[i] = -m_used; S0[i] -= delta; S1[i] -= delta; }
;             }
;             {
;                 float p[16]; float ps = 0.f;
; #pragma unroll
;                 for (int i = 0; i < 16; ++i) { p[i] = __builtin_amdgcn_exp2f(S0[i]); ps += p[i]; }
;                 if (masked) {
; #pragma unroll
;                     for (int i = 0; i < 16; ++i) p[i] = 0.f;
;                     ps = 0.f;
;                 }
;                 l += ps;
;                 const bf16x8 pk0 = pack8(p[0], p[1], p[2], p[3], p[4], p[5], p[6], p[7]);
.Lq_wd:
	s_barrier
	s_cmp_lt_u32 s57, 2
	s_cbranch_scc1 .Lq_odd_nodma
	s_cmp_gt_u32 s57, s93
	s_cbranch_scc1 .Lq_odd_nodma
	s_add_i32 s6, s57, 2
	s_and_b32 s0, s6, 3
	s_lshl_b32 s0, s0, 15
	s_add_i32 s1, s0, s33
	s_mov_b32 s7, m0
	s_lshr_b32 s0, s94, 1
	s_and_b32 s0, s0, 3
	s_lshl_b32 s95, s0, 15
	s_and_b32 s0, s57, 3
	s_lshl_b32 s58, s0, 15
	v_add_u32_e32 v203, s58, v209
	ds_read_b128 v[164:167], v203
	v_add_u32_e32 v204, s58, v210
	ds_read_b128 v[168:171], v204
	v_add_u32_e32 v192, s58, v211
	ds_read_b128 v[172:175], v192
	v_add_u32_e32 v193, s58, v212
	ds_read_b128 v[176:179], v193
	v_add_u32_e32 v208, s95, v206
	v_add_u32_e32 v213, s95, v207
	s_waitcnt lgkmcnt(4)
	v_mfma_f32_32x32x16_bf16 v[50:65], v[220:223], v[98:101], v[50:65]
	ds_read_b128 v[220:223], v208 offset:16384
	s_lshl_b32 s8, s6, 16
	s_mov_b32 s9, 0
	s_mov_b32 m0, s1
	v_lshl_add_u64 v[180:181], v[158:159], 0, s[8:9]
	global_load_lds_dwordx4 v[180:181], off
	v_max3_f32 v1, v82, v83, v84
	v_max3_f32 v1, v1, v85, v86
	v_max3_f32 v1, v1, v87, v88
	v_max3_f32 v1, v1, v89, v90
	v_max3_f32 v1, v1, v91, v92
	v_mfma_f32_32x32x16_bf16 v[34:49], v[226:229], v[98:101], v[34:49]
	ds_read_b128 v[226:229], v208 offset:20480
	s_add_i32 s8, s8, 0x80
	s_add_i32 s0, s1, 0x2000
	s_mov_b32 m0, s0
	v_lshl_add_u64 v[182:183], v[158:159], 0, s[8:9]
	global_load_lds_dwordx4 v[182:183], off
	v_max3_f32 v1, v1, v93, v94
	v_max3_f32 v1, v1, v95, v96
	v_max_f32_e32 v224, v1, v97
	v_max_f32_e32 v225, v1, v97
	v_mfma_f32_32x32x16_bf16 v[18:33], v[230:233], v[98:101], v[18:33]
	ds_read_b128 v[230:233], v208 offset:24576
	s_lshl_b32 s8, s6, 7
	s_add_i32 s0, s1, 0x4000
	s_mov_b32 m0, s0
	v_lshl_add_u64 v[184:185], v[156:157], 0, s[8:9]
	global_load_lds_dwordx4 v[184:185], off
	s_nop 1
	v_permlane32_swap_b32_e32 v224, v225
	v_max_f32_e32 v1, v224, v225
	v_cmp_lt_f32_e32 vcc, s96, v1
	s_cbranch_vccnz .Lq_re_od
.Lq_rec_od:
	v_mfma_f32_32x32x16_bf16 v[2:17], v[234:237], v[98:101], v[2:17]
	ds_read_b128 v[234:237], v208 offset:28672
	s_add_i32 s0, s1, 0x6000
	s_mov_b32 m0, s0
	v_lshl_add_u64 v[186:187], v[162:163], 0, s[8:9]
	global_load_lds_dwordx4 v[186:187], off
	s_mov_b32 m0, s7
	v_exp_f32_e32 v82, v82
	v_exp_f32_e32 v83, v83
	v_exp_f32_e32 v84, v84
	v_add_f32_e32 v251, v82, v83
	v_exp_f32_e32 v85, v85
	v_mfma_f32_32x32x16_bf16 v[50:65], v[238:241], v[102:105], v[50:65]
	ds_read_b128 v[238:241], v213 offset:16384
	v_exp_f32_e32 v86, v86
	v_add_f32_e32 v251, v251, v84
	v_exp_f32_e32 v87, v87
	v_add_f32_e32 v251, v251, v85
	v_exp_f32_e32 v88, v88
	v_mfma_f32_32x32x16_bf16 v[34:49], v[242:245], v[102:105], v[34:49]
	ds_read_b128 v[242:245], v213 offset:20480
	v_add_f32_e32 v251, v251, v86
	v_exp_f32_e32 v89, v89
	v_add_f32_e32 v251, v251, v87
	v_cvt_pk_bf16_f32 v82, v82, v83
	v_add_f32_e32 v251, v251, v88
	v_mfma_f32_32x32x16_bf16 v[18:33], v[246:249], v[102:105], v[18:33]
	ds_read_b128 v[246:249], v213 offset:24576
	v_cvt_pk_bf16_f32 v83, v84, v85
	v_cvt_pk_bf16_f32 v84, v86, v87
	v_cvt_pk_bf16_f32 v85, v88, v89
	v_add_f32_e32 v251, v251, v89
	v_mfma_f32_32x32x16_bf16 v[2:17], v[252:255], v[102:105], v[2:17]
	ds_read_b128 v[252:255], v213 offset:28672
	v_exp_f32_e32 v90, v90
	v_exp_f32_e32 v91, v91
	v_exp_f32_e32 v92, v92
	v_add_f32_e32 v251, v251, v90
	s_cmp_lg_u32 s59, 0
	s_cbranch_scc1 .Lq_rl_od
.Lq_rlc_od:
	s_waitcnt lgkmcnt(8)
	v_mfma_f32_32x32x16_bf16 v[98:113], v[164:167], v[126:129], v[66:81]
	v_exp_f32_e32 v93, v93
	v_add_f32_e32 v251, v251, v91
	v_exp_f32_e32 v94, v94
	v_add_f32_e32 v251, v251, v92
	v_mfma_f32_32x32x16_bf16 v[98:113], v[168:171], v[122:125], v[98:113]
	v_exp_f32_e32 v95, v95
	v_add_f32_e32 v251, v251, v93
	v_exp_f32_e32 v96, v96
	v_add_f32_e32 v251, v251, v94
	v_mfma_f32_32x32x16_bf16 v[98:113], v[172:175], v[118:121], v[98:113]
	v_exp_f32_e32 v97, v97
	v_add_f32_e32 v251, v251, v95
	v_cvt_pk_bf16_f32 v86, v90, v91
	v_add_f32_e32 v251, v251, v96
	v_mfma_f32_32x32x16_bf16 v[98:113], v[176:179], v[114:117], v[98:113]
	v_cvt_pk_bf16_f32 v87, v92, v93
	v_cvt_pk_bf16_f32 v88, v94, v95
	v_cvt_pk_bf16_f32 v89, v96, v97
	v_add_f32_e32 v251, v251, v97
	v_add_f32_e32 v218, v218, v251
	s_branch .Lq_odd_join
.Lq_odd_nodma:
	s_lshr_b32 s0, s94, 1
	s_and_b32 s0, s0, 3
	s_lshl_b32 s95, s0, 15
	s_and_b32 s0, s57, 3
	s_lshl_b32 s58, s0, 15
	v_add_u32_e32 v203, s58, v209
	ds_read_b128 v[164:167], v203
	v_add_u32_e32 v204, s58, v210
	ds_read_b128 v[168:171], v204
	v_add_u32_e32 v192, s58, v211
	ds_read_b128 v[172:175], v192
	v_add_u32_e32 v193, s58, v212
	ds_read_b128 v[176:179], v193
	v_add_u32_e32 v208, s95, v206
	v_add_u32_e32 v213, s95, v207
	s_waitcnt lgkmcnt(4)
	v_mfma_f32_32x32x16_bf16 v[50:65], v[220:223], v[98:101], v[50:65]
	ds_read_b128 v[220:223], v208 offset:16384
	v_max3_f32 v1, v82, v83, v84
	v_max3_f32 v1, v1, v85, v86
	v_max3_f32 v1, v1, v87, v88
	v_max3_f32 v1, v1, v89, v90
	v_max3_f32 v1, v1, v91, v92
	v_mfma_f32_32x32x16_bf16 v[34:49], v[226:229], v[98:101], v[34:49]
	ds_read_b128 v[226:229], v208 offset:20480
	v_max3_f32 v1, v1, v93, v94
	v_max3_f32 v1, v1, v95, v96
	v_max_f32_e32 v224, v1, v97
	v_max_f32_e32 v225, v1, v97
	v_mfma_f32_32x32x16_bf16 v[18:33], v[230:233], v[98:101], v[18:33]
	ds_read_b128 v[230:233], v208 offset:24576
	s_nop 1
	v_permlane32_swap_b32_e32 v224, v225
	v_max_f32_e32 v1, v224, v225
	v_cmp_lt_f32_e32 vcc, s96, v1
	s_cbranch_vccnz .Lq_re_on

; #define LAS __attribute__((address_space(3)))
; __device__ __forceinline__ void diff_unit_lds(LAS unsigned char* lds, const bf16* Qd, const bf16* Kd, const bf16* VdT, bf16* MIX, const float* ghead, float lam, int head, int u, int wave, int lane) {
;     ...
;     for (int T = 0; T < nT; ++T) {
;         LAS unsigned char* st = lds + (T & 3) * 32768;
.Lq_odd_join:
	s_add_i32 s94, s94, 1
	s_branch .Lq_even_top
